# grid barrier: non-leader workgroups poll the top-level generation word directly (one wake-up stage fewer)
# baseline (speedup 1.0000x reference)
; __device__ __forceinline__ unsigned xb_ld(unsigned* p)              { return __hip_atomic_load(p, __ATOMIC_RELAXED, __HIP_MEMORY_SCOPE_AGENT); }
; __device__ __forceinline__ unsigned xb_add(unsigned* p, unsigned v) { return __hip_atomic_fetch_add(p, v, __ATOMIC_RELAXED, __HIP_MEMORY_SCOPE_AGENT); }
; #define XB_SPIN(cond, bar) do { unsigned _sp = 0; while (cond) { __builtin_amdgcn_s_sleep(1); \
;     if ((++_sp & 255u) == 0u) { if (xb_ld(&(bar)[XB_TMO])) break; if (_sp > XB_SPIN_CAP) { atomicAdd(&(bar)[XB_TMO], 1u); break; } } } } while (0)
; __device__ __forceinline__ void xcd_barrier(unsigned* bar_in, LAS unsigned char* lds_in) {
;     ...
;         const unsigned old = xb_add(&bar[XB_XSUB(b.x)], 1u);
;         const unsigned gen = old / nloc;
;         if (old + 1u == (gen + 1u) * nloc) {
;             __builtin_amdgcn_fence(__ATOMIC_RELEASE, "agent");
;             asm volatile("s_waitcnt vmcnt(0)" ::: "memory");
;             const unsigned og = xb_add(&bar[XB_TOP], 1u);
;             const unsigned tg = og / nx;
;             if (og + 1u == (tg + 1u) * nx) xb_add(&bar[XB_TOPGEN], 1u);
;             else XB_SPIN(xb_ld(&bar[XB_TOPGEN]) == tg, bar);
;             __builtin_amdgcn_fence(__ATOMIC_ACQUIRE, "agent");
;             xb_add(&bar[XB_XGEN(b.x)], 1u);
;             asm volatile("s_waitcnt vmcnt(0)" ::: "memory");
;         } else {
;             XB_SPIN(xb_ld(&bar[XB_XGEN(b.x)]) == gen, bar);
.LBB0_679:
	s_or_b64 exec, exec, s[10:11]
	v_cvt_f32_u32_e32 v5, v3
	s_waitcnt vmcnt(0)
	v_readfirstlane_b32 s8, v4
	v_sub_u32_e32 v4, 0, v3
	v_rcp_iflag_f32_e32 v5, v5
	v_add_u32_e32 v6, s8, v0
	v_mul_f32_e32 v5, 0x4f7ffffe, v5
	v_cvt_u32_f32_e32 v5, v5
	v_mul_lo_u32 v0, v4, v5
	v_mul_hi_u32 v0, v5, v0
	v_add_u32_e32 v0, v5, v0
	v_mul_hi_u32 v0, v6, v0
	v_mul_lo_u32 v4, v0, v3
	v_sub_u32_e32 v4, v6, v4
	v_add_u32_e32 v5, 1, v0
	v_cmp_ge_u32_e32 vcc, v4, v3
	s_nop 1
	v_cndmask_b32_e32 v0, v0, v5, vcc
	v_sub_u32_e32 v5, v4, v3
	v_cndmask_b32_e32 v4, v4, v5, vcc
	v_add_u32_e32 v5, 1, v0
	v_cmp_ge_u32_e32 vcc, v4, v3
	v_add_u32_e32 v4, 1, v6
	s_nop 0
	v_cndmask_b32_e32 v0, v0, v5, vcc
	v_mul_lo_u32 v5, v3, v0
	v_add_u32_e32 v3, v5, v3
	v_cmp_ne_u32_e32 vcc, v4, v3
	s_and_saveexec_b64 s[8:9], vcc
	s_xor_b64 s[8:9], exec, s[8:9]
	s_cbranch_execz .LBB0_693
	s_waitcnt lgkmcnt(0)
	s_add_u32 s12, s70, 0x3500
	s_addc_u32 s13, s71, 0
	global_load_dword v2, v1, s[12:13] sc1
	s_waitcnt vmcnt(0)
	v_cmp_eq_u32_e32 vcc, v2, v0
	s_and_saveexec_b64 s[10:11], vcc
	s_cbranch_execz .LBB0_692
	s_mov_b32 s24, 1
	s_mov_b64 s[14:15], 0
	s_branch .LBB0_683
